# v3: + conflict-free LDS row pitch (144->160 B) for staged K/V^T tiles in mixer B/A loops
# speedup vs baseline: 1.0849x; 1.0067x over previous
.LBB0_6:
	s_waitcnt lgkmcnt(0)
	v_writelane_b32 v254, s36, 10
	s_nop 1
	v_writelane_b32 v254, s37, 11
	v_writelane_b32 v254, s38, 12
	v_writelane_b32 v254, s39, 13
	v_writelane_b32 v254, s40, 14
	v_writelane_b32 v254, s41, 15
	v_writelane_b32 v254, s42, 16
	v_writelane_b32 v254, s43, 17
	v_writelane_b32 v254, s44, 18
	v_writelane_b32 v254, s45, 19
	v_writelane_b32 v254, s46, 20
	v_writelane_b32 v254, s47, 21
	v_writelane_b32 v254, s48, 22
	v_writelane_b32 v254, s49, 23
	v_writelane_b32 v254, s50, 24
	v_writelane_b32 v254, s51, 25
	v_writelane_b32 v254, s12, 26
	s_nop 1
	v_writelane_b32 v254, s13, 27
	v_writelane_b32 v254, s14, 28
	v_writelane_b32 v254, s15, 29
	v_writelane_b32 v254, s16, 30
	v_writelane_b32 v254, s17, 31
	v_writelane_b32 v254, s18, 32
	v_writelane_b32 v254, s19, 33
	v_writelane_b32 v254, s20, 34
	v_writelane_b32 v254, s21, 35
	v_writelane_b32 v254, s22, 36
	v_writelane_b32 v254, s23, 37
	v_writelane_b32 v254, s24, 38
	v_writelane_b32 v254, s25, 39
	v_writelane_b32 v254, s26, 40
	v_writelane_b32 v254, s27, 41
	s_or_b64 exec, exec, s[2:3]
	s_load_dwordx16 s[12:27], s[0:1], 0x40
	s_cmp_lt_u32 s8, 64
	s_cselect_b64 s[0:1], -1, 0
	v_lshrrev_b32_e32 v2, 20, v0
	v_lshrrev_b32_e32 v0, 10, v0
	s_waitcnt lgkmcnt(0)
	v_writelane_b32 v254, s12, 42
	v_or_b32_e32 v0, v0, v2
	s_add_i32 s2, 0, 0x1ec00
	v_writelane_b32 v254, s13, 43
	v_writelane_b32 v254, s14, 44
	v_writelane_b32 v254, s15, 45
	v_writelane_b32 v254, s16, 46
	v_writelane_b32 v254, s17, 47
	v_writelane_b32 v254, s18, 48
	v_writelane_b32 v254, s19, 49
	v_writelane_b32 v254, s20, 50
	v_writelane_b32 v254, s21, 51
	v_writelane_b32 v254, s22, 52
	v_writelane_b32 v254, s23, 53
	v_writelane_b32 v254, s24, 54
	v_writelane_b32 v254, s25, 55
	v_writelane_b32 v254, s26, 56
	v_writelane_b32 v254, s27, 57
	v_writelane_b32 v254, s0, 4
	s_mov_b32 s93, 0
	s_ashr_i32 s62, s33, 31
	v_writelane_b32 v254, s1, 5
	s_movk_i32 s0, 0x3ff
	v_and_or_b32 v0, v0, s0, v1
	v_cmp_eq_u32_e64 s[0:1], 0, v0
	s_mov_b64 s[4:5], -1
	v_mov_b32_e32 v137, 0
	v_writelane_b32 v254, s0, 6
	s_movk_i32 s63, 0x1600
	s_movk_i32 s49, 0x80
	v_writelane_b32 v254, s1, 7
	v_writelane_b32 v254, s2, 8
	s_mov_b32 s82, 0x8000
	s_movk_i32 s83, 0x2000
	s_mov_b32 s94, 0x10000
	s_movk_i32 s95, 0x400
	s_mov_b64 s[78:79], 0x40000
	s_movk_i32 s50, 0x4000
	s_mov_b32 s51, 0x18000
	s_mov_b32 s80, 0xbfb8aa3b
	s_movk_i32 s81, 0x1ff
	s_mov_b32 s0, 0x20000
	s_mov_b32 s1, 0x30000
	s_movk_i32 s48, 0x800
	s_movk_i32 s84, 0x121
	s_movk_i32 s90, 0x1000
	s_movk_i32 s72, 0x1800
	s_mov_b32 s85, 0x5040100
	s_mov_b32 s76, 0x60000
	s_mov_b32 s70, 0x3e000000
	s_mov_b32 s71, 0xf149f2ca
	s_mov_b32 s38, 0xc2dc0000
	s_add_i32 s91, 0, 0x9000
	s_add_i32 s77, 0, 0x6800
	s_add_i32 s46, 0, 0xb800
	s_movk_i32 s47, 0x81
	s_movk_i32 s86, 0x200
	s_mov_b32 s87, 0x3e38aa3b
	s_movk_i32 s88, 0xff7f
	s_mov_b32 s89, 0xefa18f08
	v_mov_b32_e32 v241, 0xf149f2ca
	v_mov_b32_e32 v244, 0x80
	v_mov_b32_e32 v245, 0x100
	v_mov_b32_e32 v240, 0x200
	v_mov_b32_e32 v246, 0x400
	v_mov_b32_e32 v247, 0x800
	v_mov_b32_e32 v248, 0x1000
	v_mov_b32_e32 v249, 0x2000
	v_mov_b32_e32 v250, 0x4000
	v_mov_b32_e32 v251, 0x8000
	v_mov_b64_e32 v[238:239], 0x100
	v_mov_b64_e32 v[242:243], 0xff
	s_mov_b32 s34, 0
	s_mov_b64 s[96:97], 0x80
	s_mov_b32 s74, s93
	v_writelane_b32 v254, s62, 9
	s_branch .LBB0_10

.LBB0_403:
	s_and_b64 vcc, exec, s[6:7]
	s_cbranch_vccz .LBB0_412
	s_add_i32 s6, s69, 0xffffff80
	s_lshl_b32 s72, s69, 3
	s_lshr_b32 s6, s6, 5
	v_readlane_b32 s7, v255, 7
	s_bfe_u32 s10, s69, 0x40001
	s_and_b32 s8, s72, 8
	s_add_i32 s40, s6, s7
	s_add_i32 s44, s8, s73
	s_lshl_b32 s9, s10, 8
	s_add_i32 s45, s9, s44
	s_lshl_b32 s11, s40, 19
	v_and_b32_e32 v111, 15, v115
	s_add_u32 s6, s60, s11
	v_lshlrev_b32_e32 v113, 4, v111
	s_addc_u32 s7, s61, 0
	v_readlane_b32 s12, v255, 15
	v_add_u32_e32 v88, s45, v113
	s_add_u32 s38, s12, s11
	v_readlane_b32 s12, v255, 16
	s_addc_u32 s39, s12, 0
	v_readlane_b32 s12, v255, 17
	v_ashrrev_i32_e32 v89, 31, v88
	s_add_u32 s52, s12, s11
	v_readlane_b32 s11, v255, 18
	v_lshlrev_b64 v[0:1], 7, v[88:89]
	s_addc_u32 s53, s11, 0
	v_lshl_add_u64 v[32:33], s[6:7], 0, v[0:1]
	v_lshlrev_b32_e32 v0, 2, v115
	s_lshl_b32 s6, s10, 2
	v_xor_b32_e32 v109, 64, v0
	v_xor_b32_e32 v108, 0x80, v0
	v_add_u32_e32 v0, s63, v115
	s_add_i32 s7, s6, -2
	v_ashrrev_i32_e32 v112, 4, v115
	s_cmp_lg_u32 s10, 0
	v_ashrrev_i32_e32 v2, 3, v0
	v_lshlrev_b32_e32 v0, 3, v115
	v_lshlrev_b32_e32 v90, 3, v112
	s_cselect_b32 s92, s7, 0
	s_or_b32 s84, s6, 3
	v_and_b32_e32 v4, 56, v0
	s_movk_i32 s6, 0x50
	v_ashrrev_i32_e32 v91, 31, v90
	v_mad_u64_u32 v[34:35], s[6:7], v2, s6, v[4:5]
	v_lshl_add_u64 v[0:1], v[90:91], 1, v[32:33]
	s_lshl_b32 s6, s92, 6
	v_ashrrev_i32_e32 v3, 31, v2
	flat_load_dwordx4 v[16:19], v[0:1]
	flat_load_dwordx4 v[20:23], v[0:1] offset:64
	v_lshlrev_b64 v[0:1], 13, v[2:3]
	v_add_u32_e32 v2, s6, v2
	v_ashrrev_i32_e32 v3, 31, v2
	v_lshlrev_b64 v[2:3], 7, v[2:3]
	s_ashr_i32 s7, s6, 31
	v_lshl_add_u64 v[6:7], s[38:39], 0, v[2:3]
	v_lshlrev_b32_e32 v136, 1, v4
	v_lshl_add_u64 v[8:9], s[52:53], 0, v[0:1]
	v_lshl_add_u64 v[4:5], v[6:7], 0, v[136:137]
	v_lshl_add_u64 v[8:9], s[6:7], 1, v[8:9]
	flat_load_dwordx4 v[4:7], v[4:5]
	v_lshl_add_u64 v[8:9], v[8:9], 0, v[136:137]
	flat_load_dwordx4 v[8:11], v[8:9]
	s_cmp_gt_i32 s92, s84
	v_lshl_add_u32 v12, v34, 1, 0
	s_mov_b32 s78, 0
	v_lshlrev_b32_e32 v110, 2, v112
	s_waitcnt vmcnt(0) lgkmcnt(0)
	ds_write_b128 v12, v[4:7] offset:16384
	ds_write_b128 v12, v[8:11] offset:26624
	s_waitcnt lgkmcnt(0)
	s_barrier
	s_cbranch_scc1 .LBB0_616
	s_mov_b32 s41, s93
	s_lshl_b64 s[10:11], s[40:41], 19
	v_lshl_add_u64 v[2:3], s[10:11], 0, v[2:3]
	v_lshl_add_u64 v[0:1], s[10:11], 0, v[0:1]
	s_lshl_b64 s[10:11], s[6:7], 1
	v_readlane_b32 s7, v255, 41
	s_add_u32 s10, s7, s10
	v_readlane_b32 s7, v255, 42
	v_and_b32_e32 v4, 7, v115
	s_addc_u32 s11, s7, s11
	v_readlane_b32 s7, v255, 43
	v_lshlrev_b32_e32 v136, 4, v4
	s_add_i32 s7, s7, s9
	v_lshl_add_u64 v[0:1], v[0:1], 0, v[136:137]
	s_add_i32 s8, s8, s7
	v_readlane_b32 s12, v255, 39
	v_lshl_add_u64 v[38:39], s[10:11], 0, v[0:1]
	v_add_u32_e32 v0, s8, v113
	v_lshlrev_b32_e32 v1, 2, v112
	v_lshl_add_u64 v[2:3], v[2:3], 0, v[136:137]
	v_readlane_b32 s13, v255, 40
	v_sub_u32_e32 v0, v0, v1
	v_mov_b32_e32 v43, 0
	v_mul_u32_u24_e32 v35, 0xa0, v111
	v_and_b32_e32 v41, -16, v115
	v_lshl_add_u64 v[36:37], s[12:13], 0, v[2:3]
	v_subrev_u32_e32 v42, s6, v0
	v_mov_b32_e32 v40, 0xf149f2ca
	v_mov_b32_e32 v0, 0
	v_mov_b32_e32 v1, v43
	v_mov_b32_e32 v2, v43
	v_mov_b32_e32 v3, v43
	v_mov_b32_e32 v4, 0
	v_mov_b32_e32 v5, v43
	v_mov_b32_e32 v6, v43
	v_mov_b32_e32 v7, v43
	v_mov_b32_e32 v12, 0
	v_mov_b32_e32 v13, v43
	v_mov_b32_e32 v14, v43
	v_mov_b32_e32 v15, v43
	v_mov_b32_e32 v8, 0
	v_mov_b32_e32 v9, v43
	v_mov_b32_e32 v10, v43
	v_mov_b32_e32 v11, v43

.LBB0_408:
	s_add_i32 s41, 0, 0x4000
	s_cmp_eq_u32 s78, 0
	s_cselect_b64 s[58:59], -1, 0
	s_and_b64 s[6:7], s[58:59], exec
	s_cselect_b32 s6, s41, s91
	v_lshlrev_b32_e32 v44, 1, v90
	v_add3_u32 v72, s6, v35, v44
	v_add_u32_e32 v76, 51, v42
	ds_read_b128 v[44:47], v72
	ds_read_b128 v[48:51], v72 offset:2560
	ds_read_b128 v[52:55], v72 offset:5120
	v_cmp_gt_u32_e64 s[16:17], s47, v76
	v_add_u32_e32 v76, 50, v42
	v_add_u32_e32 v81, 33, v42
	v_add_u32_e32 v82, 32, v42
	v_cmp_lt_u32_e64 s[18:19], s49, v76
	v_add_u32_e32 v77, 49, v42
	v_add_u32_e32 v78, 48, v42
	v_cmp_lt_u32_e64 s[14:15], s49, v81
	v_cmp_lt_u32_e64 s[12:13], s49, v82
	v_cndmask_b32_e64 v76, 2, 0, s[18:19]
	v_cmp_lt_u32_e64 s[22:23], s49, v77
	v_cmp_lt_u32_e64 s[20:21], s49, v78
	v_cndmask_b32_e64 v81, 64, 0, s[14:15]
	v_cndmask_b32_e64 v82, v244, 0, s[12:13]
	v_cndmask_b32_e64 v77, 4, 0, s[22:23]
	v_cndmask_b32_e64 v78, 8, 0, s[20:21]
	v_add_u32_e32 v79, 35, v42
	v_add_u32_e32 v80, 34, v42
	v_or3_b32 v76, v76, v81, v82
	ds_read_b128 v[56:59], v72 offset:7680
	ds_read_b128 v[60:63], v72 offset:64
	v_cmp_lt_u32_e64 s[8:9], s49, v79
	v_cmp_lt_u32_e64 s[10:11], s49, v80
	v_or3_b32 v76, v77, v78, v76
	v_add_u32_e32 v77, 19, v42
	v_add_u32_e32 v78, 18, v42
	s_waitcnt lgkmcnt(0)
	v_mfma_f32_16x16x32_bf16 v[44:47], v[44:47], v[16:19], 0
	v_cndmask_b32_e64 v79, 16, 0, s[8:9]
	v_cndmask_b32_e64 v80, 32, 0, s[10:11]
	v_cmp_gt_u32_e32 vcc, s47, v77
	v_cmp_gt_u32_e64 s[6:7], s47, v78
	v_or3_b32 v76, v79, v80, v76
	v_cndmask_b32_e32 v77, 0, v245, vcc
	v_cndmask_b32_e64 v78, 0, v240, s[6:7]
	v_mfma_f32_16x16x32_bf16 v[48:51], v[48:51], v[16:19], 0
	v_or3_b32 v76, v77, v76, v78
	v_add_u32_e32 v77, 17, v42
	ds_read_b128 v[64:67], v72 offset:2624
	ds_read_b128 v[68:71], v72 offset:5184
	ds_read_b128 v[72:75], v72 offset:7744
	v_cmp_gt_u32_e64 s[24:25], s47, v77
	v_add_u32_e32 v78, 16, v42
	v_mfma_f32_16x16x32_bf16 v[52:55], v[52:55], v[16:19], 0
	v_cndmask_b32_e64 v77, 0, v246, s[24:25]
	v_cmp_gt_u32_e64 s[24:25], s47, v78
	v_add_u32_e32 v79, 3, v42
	v_mfma_f32_16x16x32_bf16 v[44:47], v[60:63], v[20:23], v[44:47]
	v_cndmask_b32_e64 v78, 0, v247, s[24:25]
	v_cmp_gt_u32_e64 s[24:25], s47, v79
	v_add_u32_e32 v80, 2, v42
	v_mfma_f32_16x16x32_bf16 v[56:59], v[56:59], v[16:19], 0
	v_cndmask_b32_e64 v79, 0, v248, s[24:25]
	v_cmp_gt_u32_e64 s[24:25], s47, v80
	v_add_u32_e32 v62, 1, v42
	s_waitcnt lgkmcnt(0)
	v_mfma_f32_16x16x32_bf16 v[48:51], v[64:67], v[20:23], v[48:51]
	v_cndmask_b32_e64 v60, 0, v249, s[24:25]
	v_cmp_gt_u32_e64 s[24:25], s47, v62
	v_mul_f32_e32 v44, 0x3e38aa3b, v44
	v_mfma_f32_16x16x32_bf16 v[52:55], v[68:71], v[20:23], v[52:55]
	v_cndmask_b32_e64 v62, 0, v250, s[24:25]
	v_cmp_gt_u32_e64 s[24:25], s47, v42
	v_mul_f32_e32 v45, 0x3e38aa3b, v45
	v_cndmask_b32_e64 v44, v241, v44, s[16:17]
	v_cndmask_b32_e64 v63, 0, v251, s[24:25]
	v_cndmask_b32_e64 v45, v45, v241, s[18:19]
	v_mul_f32_e32 v46, 0x3e38aa3b, v46
	v_mul_f32_e32 v47, 0x3e38aa3b, v47
	v_or_b32_e32 v77, v77, v78
	v_or_b32_e32 v62, v62, v63
	v_mfma_f32_16x16x32_bf16 v[56:59], v[72:75], v[20:23], v[56:59]
	v_max3_f32 v63, v44, s71, v45
	v_cndmask_b32_e64 v46, v46, v241, s[22:23]
	v_cndmask_b32_e64 v47, v47, v241, s[20:21]
	v_mul_f32_e32 v48, 0x3e38aa3b, v48
	v_mul_f32_e32 v49, 0x3e38aa3b, v49
	v_max3_f32 v63, v63, v46, v47
	v_cndmask_b32_e64 v48, v48, v241, s[8:9]
	v_cndmask_b32_e64 v49, v49, v241, s[10:11]
	v_mul_f32_e32 v50, 0x3e38aa3b, v50
	v_mul_f32_e32 v51, 0x3e38aa3b, v51
	v_bitop3_b32 v64, v77, s95, v76 bitop3:0xc8
	v_or_b32_e32 v78, v77, v76
	v_or_b32_e32 v60, v79, v60
	v_max3_f32 v63, v63, v48, v49
	v_cndmask_b32_e64 v50, v50, v241, s[14:15]
	v_cndmask_b32_e64 v51, v51, v241, s[12:13]
	v_mul_f32_e32 v52, 0x3e38aa3b, v52
	v_mul_f32_e32 v53, 0x3e38aa3b, v53
	v_cmp_eq_u32_e64 s[24:25], 0, v64
	v_bitop3_b32 v64, v77, s48, v76 bitop3:0xc8
	v_or_b32_e32 v61, v60, v78
	v_max3_f32 v63, v63, v50, v51
	v_cndmask_b32_e32 v52, v241, v52, vcc
	v_cndmask_b32_e64 v53, v241, v53, s[6:7]
	v_mul_f32_e32 v54, 0x3e38aa3b, v54
	v_cmp_eq_u32_e64 s[28:29], 0, v64
	v_mul_f32_e32 v55, 0x3e38aa3b, v55
	v_bitop3_b32 v64, v60, s90, v78 bitop3:0xc8
	v_bitop3_b32 v60, v60, s83, v78 bitop3:0xc8
	v_max3_f32 v63, v63, v52, v53
	v_cndmask_b32_e64 v54, v54, v241, s[24:25]
	v_cndmask_b32_e64 v55, v55, v241, s[28:29]
	v_cmp_eq_u32_e64 s[26:27], 0, v64
	v_mul_f32_e32 v56, 0x3e38aa3b, v56
	v_cmp_eq_u32_e64 s[30:31], 0, v60
	v_mul_f32_e32 v57, 0x3e38aa3b, v57
	v_max3_f32 v63, v63, v54, v55
	v_cndmask_b32_e64 v56, v56, v241, s[26:27]
	v_cndmask_b32_e64 v57, v57, v241, s[30:31]
	v_max3_f32 v60, v63, v56, v57
	v_bitop3_b32 v63, v62, s50, v61 bitop3:0xc8
	v_bitop3_b32 v61, v62, s82, v61 bitop3:0xc8
	v_cmp_eq_u32_e64 s[34:35], 0, v63
	v_mul_f32_e32 v58, 0x3e38aa3b, v58
	v_cmp_eq_u32_e64 s[36:37], 0, v61
	v_mul_f32_e32 v59, 0x3e38aa3b, v59
	v_cndmask_b32_e64 v58, v58, v241, s[34:35]
	v_cndmask_b32_e64 v59, v59, v241, s[36:37]
	v_max3_f32 v60, v60, v58, v59
	ds_bpermute_b32 v61, v109, v60
	s_cselect_b32 s79, s77, s46
	v_add3_u32 v80, s79, v41, v35
	s_waitcnt lgkmcnt(0)
	v_max_f32_e32 v61, v61, v61
	v_max_f32_e32 v72, v60, v61
	ds_bpermute_b32 v73, v108, v72
	ds_read_b128 v[60:63], v80
	ds_read_b128 v[64:67], v80 offset:64
	ds_read_b128 v[68:71], v80 offset:2560
	s_waitcnt lgkmcnt(0)
	v_max3_f32 v118, v40, v72, v73
	v_sub_f32_e32 v44, v44, v118
	v_sub_f32_e32 v45, v45, v118
	v_sub_f32_e32 v46, v46, v118
	v_sub_f32_e32 v47, v47, v118
	v_sub_f32_e32 v48, v48, v118
	v_sub_f32_e32 v49, v49, v118
	v_sub_f32_e32 v50, v50, v118
	v_sub_f32_e32 v51, v51, v118
	v_sub_f32_e32 v40, v40, v118
	v_exp_f32_e32 v44, v44
	v_exp_f32_e32 v45, v45
	v_exp_f32_e32 v46, v46
	v_exp_f32_e32 v47, v47
	v_exp_f32_e32 v48, v48
	v_exp_f32_e32 v49, v49
	v_exp_f32_e32 v50, v50
	v_exp_f32_e32 v51, v51
	v_exp_f32_e32 v40, v40
	v_cndmask_b32_e64 v44, 0, v44, s[16:17]
	v_cndmask_b32_e64 v45, v45, 0, s[18:19]
	v_cndmask_b32_e64 v46, v46, 0, s[22:23]
	v_cndmask_b32_e64 v47, v47, 0, s[20:21]
	v_cndmask_b32_e64 v48, v48, 0, s[8:9]
	v_cndmask_b32_e64 v49, v49, 0, s[10:11]
	v_cndmask_b32_e64 v50, v50, 0, s[14:15]
	v_cndmask_b32_e64 v51, v51, 0, s[12:13]
	v_sub_f32_e32 v52, v52, v118
	v_sub_f32_e32 v53, v53, v118
	v_sub_f32_e32 v54, v54, v118
	v_sub_f32_e32 v55, v55, v118
	v_sub_f32_e32 v56, v56, v118
	v_sub_f32_e32 v57, v57, v118
	v_sub_f32_e32 v58, v58, v118
	v_sub_f32_e32 v59, v59, v118
	v_exp_f32_e32 v52, v52
	v_exp_f32_e32 v53, v53
	v_exp_f32_e32 v54, v54
	v_exp_f32_e32 v55, v55
	v_exp_f32_e32 v56, v56
	v_exp_f32_e32 v57, v57
	v_exp_f32_e32 v58, v58
	v_exp_f32_e32 v59, v59
	v_cvt_pk_bf16_f32 v72, v44, v45
	v_cvt_pk_bf16_f32 v73, v46, v47
	v_cvt_pk_bf16_f32 v74, v48, v49
	v_cvt_pk_bf16_f32 v75, v50, v51
	v_pk_mul_f32 v[10:11], v[10:11], v[40:41] op_sel_hi:[1,0]
	v_pk_mul_f32 v[8:9], v[8:9], v[40:41] op_sel_hi:[1,0]
	v_cndmask_b32_e32 v52, 0, v52, vcc
	v_cndmask_b32_e64 v53, 0, v53, s[6:7]
	v_mfma_f32_16x16x32_bf16 v[8:11], v[60:63], v[72:75], v[8:11]
	ds_read_b128 v[60:63], v80 offset:2624
	v_cndmask_b32_e64 v54, v54, 0, s[24:25]
	v_cndmask_b32_e64 v55, v55, 0, s[28:29]
	v_cndmask_b32_e64 v56, v56, 0, s[26:27]
	v_cndmask_b32_e64 v57, v57, 0, s[30:31]
	v_cndmask_b32_e64 v58, v58, 0, s[34:35]
	v_cndmask_b32_e64 v59, v59, 0, s[36:37]
	v_cvt_pk_bf16_f32 v76, v52, v53
	v_cvt_pk_bf16_f32 v77, v54, v55
	v_cvt_pk_bf16_f32 v78, v56, v57
	v_cvt_pk_bf16_f32 v79, v58, v59
	v_pk_mul_f32 v[14:15], v[14:15], v[40:41] op_sel_hi:[1,0]
	v_pk_mul_f32 v[12:13], v[12:13], v[40:41] op_sel_hi:[1,0]
	v_mfma_f32_16x16x32_bf16 v[8:11], v[64:67], v[76:79], v[8:11]
	ds_read_b128 v[64:67], v80 offset:5120
	v_pk_mul_f32 v[6:7], v[6:7], v[40:41] op_sel_hi:[1,0]
	v_pk_mul_f32 v[4:5], v[4:5], v[40:41] op_sel_hi:[1,0]
	v_mfma_f32_16x16x32_bf16 v[12:15], v[68:71], v[72:75], v[12:15]
	v_mul_f32_e64 v2, v2, v40
	v_mul_f32_e64 v3, v3, v40
	v_pk_mul_f32 v[0:1], v[0:1], v[40:41] op_sel_hi:[1,0]
	s_andn2_b64 vcc, exec, s[56:57]
	s_waitcnt lgkmcnt(0)
	v_mfma_f32_16x16x32_bf16 v[12:15], v[60:63], v[76:79], v[12:15]
	ds_read_b128 v[60:63], v80 offset:5184
	v_mfma_f32_16x16x32_bf16 v[4:7], v[64:67], v[72:75], v[4:7]
	ds_read_b128 v[64:67], v80 offset:7680
	s_waitcnt lgkmcnt(0)
	v_mfma_f32_16x16x32_bf16 v[4:7], v[60:63], v[76:79], v[4:7]
	ds_read_b128 v[60:63], v80 offset:7744
	v_mfma_f32_16x16x32_bf16 v[0:3], v[64:67], v[72:75], v[0:3]
	s_waitcnt lgkmcnt(0)
	v_mfma_f32_16x16x32_bf16 v[0:3], v[60:63], v[76:79], v[0:3]
	s_cbranch_vccnz .LBB0_410
	s_and_b64 s[6:7], s[58:59], exec
	s_cselect_b32 s6, s91, s41
	v_lshlrev_b32_e32 v60, 1, v34
	v_add_u32_e32 v61, s6, v60
	s_cselect_b32 s6, s46, s77
	v_add_u32_e32 v60, s6, v60
	s_waitcnt vmcnt(0)
	ds_write_b128 v61, v[28:31]
	ds_write_b128 v60, v[24:27]

.LBB0_566:
	s_or_b64 exec, exec, s[14:15]
	ds_read_b128 v[28:31], v137 offset:8192
	ds_read_b128 v[32:35], v137 offset:8208
	ds_read_b128 v[56:59], v137 offset:8224
	ds_read_b128 v[60:63], v137 offset:8240
	s_lshr_b32 s44, s58, 6
	s_waitcnt lgkmcnt(3)
	v_readfirstlane_b32 s15, v29
	v_readfirstlane_b32 s14, v28
	v_readfirstlane_b32 s19, v31
	v_readfirstlane_b32 s18, v30
	s_or_b64 s[14:15], s[18:19], s[14:15]
	s_waitcnt lgkmcnt(2)
	v_readfirstlane_b32 s19, v33
	v_readfirstlane_b32 s18, v32
	v_readfirstlane_b32 s21, v35
	v_readfirstlane_b32 s20, v34
	s_or_b64 s[14:15], s[14:15], s[18:19]
	s_or_b64 s[14:15], s[14:15], s[20:21]
	s_waitcnt lgkmcnt(1)
	v_readfirstlane_b32 s19, v57
	v_readfirstlane_b32 s18, v56
	v_readfirstlane_b32 s21, v59
	v_readfirstlane_b32 s20, v58
	s_or_b64 s[14:15], s[14:15], s[18:19]
	s_or_b64 s[14:15], s[14:15], s[20:21]
	s_waitcnt lgkmcnt(0)
	v_readfirstlane_b32 s19, v61
	v_readfirstlane_b32 s18, v60
	v_readfirstlane_b32 s21, v63
	v_readfirstlane_b32 s20, v62
	s_or_b64 s[14:15], s[14:15], s[18:19]
	s_or_b64 s[14:15], s[14:15], s[20:21]
	s_lshl_b64 s[18:19], 2, s44
	s_add_u32 s18, s18, -1
	s_addc_u32 s19, s19, -1
	s_cmpk_lt_u32 s58, 0xfc0
	s_cselect_b32 s19, s19, -1
	s_cselect_b32 s18, s18, -1
	s_and_b64 s[20:21], s[14:15], s[18:19]
	s_cmp_lg_u64 s[20:21], 0
	s_cselect_b64 s[18:19], -1, 0
	s_cmp_eq_u64 s[20:21], 0
	s_mov_b64 s[14:15], 0
	s_cbranch_scc1 .LBB0_582
	s_add_u32 s14, s20, -1
	s_addc_u32 s15, s21, -1
	s_ff1_i32_b64 s22, s[20:21]
	s_and_b64 s[14:15], s[14:15], s[20:21]
	s_movk_i32 s20, 0x50
	v_mad_u64_u32 v[28:29], s[20:21], v120, s20, v[124:125]
	v_lshl_add_u32 v28, v28, 1, 0
	ds_write_b128 v28, v[20:23] offset:16384
	ds_write_b128 v28, v[24:27] offset:26624
	s_branch .LBB0_583

.LBB0_583:
	s_and_b64 vcc, exec, s[18:19]
	v_lshlrev_b32_e32 v24, 3, v125
	s_movk_i32 s18, 0xa0
	v_cvt_pk_bf16_f32 v20, v48, v50
	v_cvt_pk_bf16_f32 v21, v52, v36
	v_cvt_pk_bf16_f32 v22, v40, v42
	v_cvt_pk_bf16_f32 v23, v44, v38
	v_mul_lo_u32 v148, v54, s18
	v_lshlrev_b32_e32 v149, 4, v125
	v_lshlrev_b32_e32 v135, 2, v125
	v_lshlrev_b32_e32 v150, 1, v24
	s_waitcnt lgkmcnt(0)
	s_barrier
	s_cbranch_vccz .LBB0_615
	v_mov_b32_e32 v24, s13
	v_mov_b32_e32 v25, s11
	v_cmp_eq_u32_e32 vcc, 2, v218
	v_mov_b32_e32 v26, s10
	v_mov_b32_e32 v60, v137
	v_cndmask_b32_e32 v24, v24, v25, vcc
	v_mov_b32_e32 v25, s12
	v_cndmask_b32_e32 v25, v25, v26, vcc
	v_mov_b32_e32 v26, s8
	v_cmp_eq_u32_e32 vcc, 1, v218
	v_mov_b32_e32 v61, v137
	v_mov_b32_e32 v62, v137
	v_cndmask_b32_e32 v25, v25, v26, vcc
	v_mov_b32_e32 v26, s9
	v_cndmask_b32_e32 v24, v24, v26, vcc
	v_mov_b32_e32 v26, s7
	v_cmp_gt_u32_e32 vcc, 4, v121
	v_mov_b32_e32 v63, v137
	v_mov_b32_e32 v121, 0
	v_cndmask_b32_e32 v115, v24, v26, vcc
	v_mov_b32_e32 v24, s6
	s_movk_i32 s6, 0x50
	v_mov_b64_e32 v[56:57], v[60:61]
	v_mov_b64_e32 v[52:53], v[60:61]
	v_mov_b64_e32 v[48:49], v[60:61]
	v_lshl_add_u64 v[132:133], s[64:65], 0, v[136:137]
	v_cndmask_b32_e32 v134, v25, v24, vcc
	s_or_b64 s[38:39], s[16:17], s[12:13]
	v_mad_u64_u32 v[130:131], s[6:7], v120, s6, v[124:125]
	s_mov_b32 s45, 0
	v_mov_b32_e32 v125, 0xf149f2ca
	v_mov_b64_e32 v[58:59], v[62:63]
	v_mov_b64_e32 v[54:55], v[62:63]
	v_mov_b64_e32 v[50:51], v[62:63]
	v_mov_b32_e32 v36, 0
	v_mov_b32_e32 v37, v121
	v_mov_b32_e32 v38, v121
	v_mov_b32_e32 v39, v121
	v_mov_b32_e32 v32, 0
	v_mov_b32_e32 v33, v121
	v_mov_b32_e32 v34, v121
	v_mov_b32_e32 v35, v121
	v_mov_b32_e32 v28, 0
	v_mov_b32_e32 v29, v121
	v_mov_b32_e32 v30, v121
	v_mov_b32_e32 v31, v121
	v_mov_b32_e32 v24, 0
	v_mov_b32_e32 v25, v121
	v_mov_b32_e32 v26, v121
	v_mov_b32_e32 v27, v121

.LBB0_587:
	s_lshl_b64 s[6:7], 1, s22
	s_and_b64 s[8:9], s[6:7], s[38:39]
	s_cmp_eq_u64 s[8:9], 0
	s_cbranch_scc1 .LBB0_597
	s_add_i32 s8, 0, 0x4000
	s_cmp_eq_u32 s45, 0
	s_cselect_b32 s8, s8, s91
	v_add3_u32 v64, s8, v148, v150
	ds_read_b128 v[24:27], v64
	ds_read_b128 v[28:31], v64 offset:64
	ds_read_b128 v[32:35], v64 offset:2560
	ds_read_b128 v[36:39], v64 offset:2624
	s_cselect_b32 s8, s77, s46
	s_cmp_eq_u32 s22, 0
	s_waitcnt lgkmcnt(0)
	v_mfma_f32_16x16x32_bf16 v[24:27], v[24:27], v[20:23], 0
	v_mfma_f32_16x16x32_bf16 v[32:35], v[32:35], v[20:23], 0
	v_mfma_f32_16x16x32_bf16 v[108:111], v[28:31], v[0:3], v[24:27]
	s_nop 5
	ds_read_b128 v[24:27], v64 offset:5120
	ds_read_b128 v[28:31], v64 offset:5184
	v_mfma_f32_16x16x32_bf16 v[104:107], v[36:39], v[0:3], v[32:35]
	s_nop 2
	ds_read_b128 v[32:35], v64 offset:7680
	ds_read_b128 v[36:39], v64 offset:7744
	v_add3_u32 v64, s8, v149, v148
	ds_read_b128 v[92:95], v64
	ds_read_b128 v[88:91], v64 offset:64
	s_waitcnt lgkmcnt(0)
	v_mfma_f32_16x16x32_bf16 v[24:27], v[24:27], v[20:23], 0
	ds_read_b128 v[84:87], v64 offset:2560
	ds_read_b128 v[80:83], v64 offset:2624
	ds_read_b128 v[76:79], v64 offset:5120
	ds_read_b128 v[72:75], v64 offset:5184
	ds_read_b128 v[68:71], v64 offset:7680
	ds_read_b128 v[64:67], v64 offset:7744
	s_cselect_b64 s[8:9], -1, 0
	v_mfma_f32_16x16x32_bf16 v[100:103], v[28:31], v[0:3], v[24:27]
	s_and_b64 vcc, exec, s[8:9]
	v_mfma_f32_16x16x32_bf16 v[24:27], v[32:35], v[20:23], 0
	v_mfma_f32_16x16x32_bf16 v[96:99], v[36:39], v[0:3], v[24:27]
	s_cbranch_vccnz .LBB0_591
	s_lshl_b32 s8, s22, 6
	s_or_b32 s8, s8, 63
	s_cmp_le_i32 s8, s56
	s_mov_b64 s[8:9], -1
	s_cbranch_scc0 .LBB0_592
	s_nop 0
	v_and_b32_e32 v25, s7, v115
	v_and_b32_e32 v24, s6, v134
	v_cmp_eq_u64_e32 vcc, 0, v[24:25]
	s_mov_b64 s[8:9], 0
	s_nop 0
	v_cndmask_b32_e32 v24, 0, v241, vcc
	v_fmamk_f32 v25, v108, 0x3e38aa3b, v24
	v_fmamk_f32 v26, v109, 0x3e38aa3b, v24
	v_max3_f32 v27, v25, s71, v26
	v_fmamk_f32 v28, v110, 0x3e38aa3b, v24
	v_fmamk_f32 v29, v111, 0x3e38aa3b, v24
	v_max3_f32 v27, v27, v28, v29
	v_fmamk_f32 v30, v104, 0x3e38aa3b, v24
	v_fmamk_f32 v31, v105, 0x3e38aa3b, v24
	v_max3_f32 v27, v27, v30, v31
	v_fmamk_f32 v32, v106, 0x3e38aa3b, v24
	v_fmamk_f32 v33, v107, 0x3e38aa3b, v24
	v_max3_f32 v27, v27, v32, v33
	v_fmamk_f32 v34, v100, 0x3e38aa3b, v24
	v_fmamk_f32 v35, v101, 0x3e38aa3b, v24
	v_max3_f32 v27, v27, v34, v35
	v_fmamk_f32 v36, v102, 0x3e38aa3b, v24
	v_fmamk_f32 v37, v103, 0x3e38aa3b, v24
	v_max3_f32 v27, v27, v36, v37
	v_fmamk_f32 v38, v96, 0x3e38aa3b, v24
	v_fmamk_f32 v39, v97, 0x3e38aa3b, v24
	v_max3_f32 v27, v27, v38, v39
	v_fmamk_f32 v131, v98, 0x3e38aa3b, v24
	v_fmac_f32_e32 v24, 0x3e38aa3b, v99
	v_max3_f32 v27, v27, v131, v24
	v_mov_b32_e32 v127, v27
	s_nop 1
	v_permlane16_swap_b32_e32 v27, v127
	v_max_f32_e32 v27, v27, v127
	v_mov_b32_e32 v127, v27
	s_nop 1
	v_permlane32_swap_b32_e32 v27, v127
	v_max3_f32 v127, v125, v27, v127
	v_sub_f32_e32 v25, v25, v127
	v_exp_f32_e32 v25, v25
	v_sub_f32_e32 v26, v26, v127
	v_exp_f32_e32 v26, v26
	v_sub_f32_e32 v28, v28, v127
	v_exp_f32_e32 v28, v28
	v_sub_f32_e32 v29, v29, v127
	v_exp_f32_e32 v29, v29
	v_sub_f32_e32 v30, v30, v127
	v_add_f32_e32 v138, 0, v25
	v_exp_f32_e32 v30, v30
	v_sub_f32_e32 v31, v31, v127
	v_add_f32_e32 v138, v26, v138
	v_exp_f32_e32 v31, v31
	v_sub_f32_e32 v32, v32, v127
	v_add_f32_e32 v138, v28, v138
	v_exp_f32_e32 v32, v32
	v_sub_f32_e32 v33, v33, v127
	v_add_f32_e32 v138, v29, v138
	v_exp_f32_e32 v33, v33
	v_sub_f32_e32 v34, v34, v127
	v_add_f32_e32 v138, v30, v138
	v_exp_f32_e32 v34, v34
	v_sub_f32_e32 v35, v35, v127
	v_add_f32_e32 v138, v31, v138
	v_exp_f32_e32 v35, v35
	v_sub_f32_e32 v36, v36, v127
	v_add_f32_e32 v138, v32, v138
	v_exp_f32_e32 v139, v36
	v_sub_f32_e32 v37, v37, v127
	v_add_f32_e32 v138, v33, v138
	v_exp_f32_e32 v140, v37
	v_sub_f32_e32 v37, v38, v127
	v_add_f32_e32 v138, v34, v138
	v_exp_f32_e32 v141, v37
	v_sub_f32_e32 v37, v39, v127
	v_add_f32_e32 v138, v35, v138
	v_exp_f32_e32 v143, v37
	v_sub_f32_e32 v37, v131, v127
	v_add_f32_e32 v36, v139, v138
	v_exp_f32_e32 v144, v37
	v_sub_f32_e32 v24, v24, v127
	v_sub_f32_e32 v27, v125, v127
	v_add_f32_e32 v36, v140, v36
	v_exp_f32_e32 v24, v24
	v_add_f32_e32 v36, v141, v36
	v_exp_f32_e32 v142, v27
	v_add_f32_e32 v36, v143, v36
	v_add_f32_e32 v36, v144, v36
	v_add_f32_e32 v131, v24, v36
	v_fmac_f32_e32 v131, v121, v142
	v_cvt_pk_bf16_f32 v36, v25, v26
	v_cvt_pk_bf16_f32 v37, v28, v29
	v_cvt_pk_bf16_f32 v38, v30, v31
	v_cvt_pk_bf16_f32 v39, v32, v33
	v_cvt_pk_bf16_f32 v138, v34, v35
	v_cvt_pk_bf16_f32 v139, v139, v140
	v_cvt_pk_bf16_f32 v140, v141, v143
	v_cvt_pk_bf16_f32 v141, v144, v24
	v_pk_mul_f32 v[26:27], v[62:63], v[142:143] op_sel_hi:[1,0]
	v_pk_mul_f32 v[24:25], v[60:61], v[142:143] op_sel_hi:[1,0]
	v_pk_mul_f32 v[30:31], v[58:59], v[142:143] op_sel_hi:[1,0]
	v_pk_mul_f32 v[28:29], v[56:57], v[142:143] op_sel_hi:[1,0]
	v_pk_mul_f32 v[34:35], v[54:55], v[142:143] op_sel_hi:[1,0]
	v_pk_mul_f32 v[32:33], v[52:53], v[142:143] op_sel_hi:[1,0]
	v_pk_mul_f32 v[144:145], v[50:51], v[142:143] op_sel_hi:[1,0]
	v_pk_mul_f32 v[142:143], v[48:49], v[142:143] op_sel_hi:[1,0]
	s_waitcnt lgkmcnt(0)
	v_mfma_f32_16x16x32_bf16 v[24:27], v[92:95], v[36:39], v[24:27]
	v_mfma_f32_16x16x32_bf16 v[28:31], v[84:87], v[36:39], v[28:31]
	v_mfma_f32_16x16x32_bf16 v[32:35], v[76:79], v[36:39], v[32:35]
	v_mfma_f32_16x16x32_bf16 v[36:39], v[68:71], v[36:39], v[142:145]
	v_mfma_f32_16x16x32_bf16 v[24:27], v[88:91], v[138:141], v[24:27]
	v_mfma_f32_16x16x32_bf16 v[28:31], v[80:83], v[138:141], v[28:31]
	v_mfma_f32_16x16x32_bf16 v[32:35], v[72:75], v[138:141], v[32:35]
	v_mfma_f32_16x16x32_bf16 v[36:39], v[64:67], v[138:141], v[36:39]
	s_branch .LBB0_592

.LBB0_602:
	s_movk_i32 s6, 0x50
	v_mov_b32_e32 v121, 0
	v_mad_u64_u32 v[130:131], s[6:7], v120, s6, v[124:125]
	v_mov_b32_e32 v36, 0
	v_mov_b32_e32 v37, v121
	v_mov_b32_e32 v38, v121
	v_mov_b32_e32 v39, v121
	v_mov_b32_e32 v32, 0
	v_mov_b32_e32 v33, v121
	v_mov_b32_e32 v34, v121
	v_mov_b32_e32 v35, v121
	v_mov_b32_e32 v28, 0
	v_mov_b32_e32 v29, v121
	v_mov_b32_e32 v30, v121
	v_mov_b32_e32 v31, v121
	v_mov_b32_e32 v24, 0
	v_mov_b32_e32 v25, v121
	v_mov_b32_e32 v26, v121
	v_mov_b32_e32 v27, v121
.LBB0_603:
	s_waitcnt vmcnt(0)
	ds_bpermute_b32 v40, v216, v121
	s_sub_i32 s6, 0xde0, s57
	s_lshr_b32 s6, s6, 6
	s_cmpk_gt_u32 s58, 0x1ff
	s_cselect_b32 s45, s6, 0
	s_lshl_b32 s92, s45, 6
	s_waitcnt lgkmcnt(0)
	v_add_f32_e32 v121, v121, v40
	v_add_u32_e32 v40, s92, v120
	v_ashrrev_i32_e32 v41, 31, v40
	v_lshlrev_b64 v[40:41], 7, v[40:41]
	v_lshl_add_u64 v[40:41], s[66:67], 0, v[40:41]
	v_readlane_b32 s6, v255, 37
	v_lshl_add_u64 v[40:41], v[40:41], 0, v[136:137]
	v_readlane_b32 s7, v255, 38
	flat_load_dwordx4 v[42:45], v[40:41]
	ds_bpermute_b32 v125, v217, v121
	v_lshl_add_u64 v[40:41], s[6:7], 0, v[122:123]
	v_lshl_add_u64 v[46:47], s[92:93], 1, v[40:41]
	v_lshl_add_u64 v[46:47], v[46:47], 0, v[136:137]
	flat_load_dwordx4 v[46:49], v[46:47]
	v_mov_b32_e32 v83, 0
	v_lshl_add_u32 v50, v130, 1, 0
	s_cmp_gt_u32 s45, s44
	v_mov_b32_e32 v82, v83
	v_mov_b32_e32 v81, v83
	v_mov_b32_e32 v80, v83
	v_mov_b32_e32 v95, v83
	v_mov_b32_e32 v94, v83
	v_mov_b32_e32 v93, v83
	v_mov_b32_e32 v92, v83
	v_mov_b32_e32 v107, v83
	v_mov_b32_e32 v106, v83
	v_mov_b32_e32 v105, v83
	v_mov_b32_e32 v104, v83
	v_mov_b32_e32 v111, v83
	v_mov_b32_e32 v110, v83
	v_mov_b32_e32 v109, v83
	v_mov_b32_e32 v108, v83
	v_mov_b32_e32 v151, v83
	s_waitcnt vmcnt(0) lgkmcnt(0)
	ds_write_b128 v50, v[42:45] offset:16384
	ds_write_b128 v50, v[46:49] offset:26624
	s_waitcnt lgkmcnt(0)
	s_barrier
	s_cbranch_scc1 .LBB0_385
	v_readlane_b32 s6, v255, 46
	v_lshl_add_u64 v[126:127], v[40:41], 0, v[136:137]
	v_mov_b32_e32 v124, 0
	v_add_u32_e32 v40, s6, v218
	v_sub_u32_e32 v40, v40, v135
	v_subrev_u32_e32 v40, s57, v40
	v_lshl_add_u64 v[122:123], s[66:67], 0, v[136:137]
	s_add_i32 s54, s56, 0xfffffe04
	v_add_u32_e32 v115, 64, v120
	v_subrev_u32_e32 v120, s92, v40
	v_mov_b32_e32 v136, 0xf149f2ca
	s_mov_b32 s55, 0
	v_mov_b32_e32 v144, 0
	v_mov_b32_e32 v145, v124
	v_mov_b32_e32 v146, 0
	v_mov_b32_e32 v147, v124
	v_mov_b32_e32 v140, 0
	v_mov_b32_e32 v141, v124
	v_mov_b32_e32 v142, 0
	v_mov_b32_e32 v143, v124
	v_mov_b32_e32 v134, 0
	v_mov_b32_e32 v135, v124
	v_mov_b32_e32 v138, 0
	v_mov_b32_e32 v139, v124
	v_mov_b32_e32 v128, 0
	v_mov_b32_e32 v129, v124
	v_mov_b32_e32 v132, 0
	v_mov_b32_e32 v133, v124

.LBB0_607:
	s_add_i32 s57, 0, 0x4000
	s_cmp_eq_u32 s55, 0
	s_cselect_b64 s[52:53], -1, 0
	s_and_b64 s[6:7], s[52:53], exec
	s_cselect_b32 s6, s57, s91
	v_add3_u32 v72, s6, v148, v150
	ds_read_b128 v[48:51], v72
	ds_read_b128 v[52:55], v72 offset:64
	ds_read_b128 v[56:59], v72 offset:2560
	ds_read_b128 v[60:63], v72 offset:2624
	ds_read_b128 v[64:67], v72 offset:5120
	ds_read_b128 v[68:71], v72 offset:5184
	s_cselect_b32 s6, s77, s46
	s_waitcnt lgkmcnt(0)
	v_mfma_f32_16x16x32_bf16 v[48:51], v[48:51], v[20:23], 0
	v_add3_u32 v92, s6, v149, v148
	s_cmp_lt_i32 s92, s54
	s_cselect_b64 s[6:7], -1, 0
	v_mfma_f32_16x16x32_bf16 v[100:103], v[52:55], v[0:3], v[48:51]
	ds_read_b128 v[80:83], v72 offset:7744
	s_add_i32 s8, s92, 63
	s_cmp_gt_i32 s8, s56
	s_nop 0
	ds_read_b128 v[48:51], v72 offset:7680
	v_mfma_f32_16x16x32_bf16 v[56:59], v[56:59], v[20:23], 0
	s_cselect_b64 s[8:9], -1, 0
	s_or_b64 s[6:7], s[6:7], s[8:9]
	s_andn2_b64 vcc, exec, s[6:7]
	v_mfma_f32_16x16x32_bf16 v[64:67], v[64:67], v[20:23], 0
	s_mov_b64 s[6:7], -1
	s_waitcnt lgkmcnt(0)
	v_mfma_f32_16x16x32_bf16 v[84:87], v[48:51], v[20:23], 0
	v_mfma_f32_16x16x32_bf16 v[96:99], v[60:63], v[0:3], v[56:59]
	v_mfma_f32_16x16x32_bf16 v[88:91], v[68:71], v[0:3], v[64:67]
	ds_read_b128 v[76:79], v92
	ds_read_b128 v[72:75], v92 offset:64
	ds_read_b128 v[68:71], v92 offset:2560
	ds_read_b128 v[64:67], v92 offset:2624
	ds_read_b128 v[60:63], v92 offset:5120
	ds_read_b128 v[56:59], v92 offset:5184
	ds_read_b128 v[52:55], v92 offset:7680
	ds_read_b128 v[48:51], v92 offset:7744
	v_mfma_f32_16x16x32_bf16 v[84:87], v[80:83], v[0:3], v[84:87]
	s_cbranch_vccnz .LBB0_613
	s_andn2_b64 vcc, exec, s[6:7]
	s_cbranch_vccz .LBB0_614
